# FoX: running row max subtracted from the bias-initialised score accumulators in the MFMA half (32 v_sub moved out of the softmax half), softmax works on s-m with rescale on max(s-m)>8, in-place exp /
# baseline (speedup 1.0000x reference)
.Lfx_body:
	s_cmp_lt_u32 s62, 0x4000005e
	s_cselect_b64 s[78:79], -1, 0
	s_andn2_b64 vcc, exec, s[78:79]
	s_cbranch_vccnz .Lfx_h1_done
	s_andn2_b64 vcc, exec, s[80:81]
	s_cbranch_vccnz .Lfx_h1_qonly
	s_add_i32 s64, s77, s51
	v_add_u32_e32 v10, s64, v183
	v_add_u32_e32 v11, s64, v184
	v_add_u32_e32 v12, s64, v185
	v_add_u32_e32 v13, s64, v186
	s_add_i32 s65, s76, s51
	v_add_u32_e32 v14, s65, v174
	s_lshl_b32 s66, s50, 2
	s_add_i32 s66, s66, s76
	v_lshl_add_u32 v0, v144, 2, s66
	v_add_u32_e32 v0, 0x10000, v0
	s_waitcnt lgkmcnt(6)
	v_mfma_f32_32x32x16_bf16 v[64:79], v[2:5], v[196:199], v[64:79]
	ds_read_b64_tr_b16 v[220:221], v11 offset:32768
	ds_read_b64_tr_b16 v[222:223], v11 offset:34816
	s_lshl_b32 s64, s41, 7
	s_add_i32 s66, s64, 0xffffff80
	s_max_i32 s66, s66, 0
	s_mov_b32 s67, 0
	s_lshl_b64 s[28:29], s[66:67], 8
	s_add_u32 s28, s27, s28
	s_addc_u32 s29, s38, s29
	s_lshl_b64 s[68:69], s[66:67], 2
	s_add_u32 s68, s70, s68
	s_addc_u32 s69, s71, s69
	s_lshl_b64 s[30:31], s[66:67], 8
	s_add_u32 s30, s23, s30
	s_addc_u32 s31, s24, s31
	ds_read_b128 v[96:99], v0
	s_waitcnt lgkmcnt(7)
	v_mfma_f32_32x32x16_bf16 v[64:79], v[6:9], v[204:207], v[64:79]
	ds_read_b64_tr_b16 v[224:225], v11 offset:36864
	ds_read_b64_tr_b16 v[226:227], v11 offset:38912
	s_add_i32 s33, s73, s77
	s_mov_b32 m0, s33
	s_nop 0
	global_load_lds_dwordx4 v163, s[28:29]
	ds_read_b128 v[100:103], v0 offset:32
	s_waitcnt lgkmcnt(8)
	v_mfma_f32_32x32x16_bf16 v[64:79], v[212:215], v[200:203], v[64:79]
	ds_read_b64_tr_b16 v[228:229], v11 offset:40960
	ds_read_b64_tr_b16 v[230:231], v11 offset:43008
	ds_read_b128 v[80:83], v0 offset:128
	s_waitcnt lgkmcnt(9)
	v_mfma_f32_32x32x16_bf16 v[64:79], v[216:219], v[208:211], v[64:79]
	ds_read_b64_tr_b16 v[232:233], v11 offset:45056
	ds_read_b64_tr_b16 v[234:235], v11 offset:47104
	ds_read_b128 v[84:87], v0 offset:160
	s_waitcnt lgkmcnt(10)
	v_mfma_f32_32x32x16_bf16 v[48:63], v[220:223], v[196:199], v[48:63]
	ds_read_b64_tr_b16 v[2:3], v12 offset:32768
	ds_read_b64_tr_b16 v[4:5], v12 offset:34816
	s_add_i32 m0, s33, 0x400
	s_nop 0
	global_load_lds_dwordx4 v189, s[28:29]
	ds_read_b128 v[104:107], v0 offset:64
	s_waitcnt lgkmcnt(10)
	v_mfma_f32_32x32x16_bf16 v[48:63], v[224:227], v[204:207], v[48:63]
	ds_read_b64_tr_b16 v[6:7], v12 offset:36864
	ds_read_b64_tr_b16 v[8:9], v12 offset:38912
	ds_read_b128 v[108:111], v0 offset:96
	v_sub_f32_e32 v96, v96, v192
	v_sub_f32_e32 v97, v97, v192
	v_sub_f32_e32 v98, v98, v192
	v_sub_f32_e32 v99, v99, v192
	s_waitcnt lgkmcnt(10)
	v_mfma_f32_32x32x16_bf16 v[48:63], v[228:231], v[200:203], v[48:63]
	ds_read_b64_tr_b16 v[212:213], v12 offset:40960
	ds_read_b64_tr_b16 v[214:215], v12 offset:43008
	ds_read_b128 v[88:91], v0 offset:192
	v_sub_f32_e32 v100, v100, v192
	v_sub_f32_e32 v101, v101, v192
	v_sub_f32_e32 v102, v102, v192
	v_sub_f32_e32 v103, v103, v192
	s_waitcnt lgkmcnt(10)
	v_mfma_f32_32x32x16_bf16 v[48:63], v[232:235], v[208:211], v[48:63]
	ds_read_b64_tr_b16 v[216:217], v12 offset:45056
	ds_read_b64_tr_b16 v[218:219], v12 offset:47104
	s_add_i32 m0, s33, 0x800
	s_nop 0
	global_load_lds_dwordx4 v190, s[28:29]
	ds_read_b128 v[92:95], v0 offset:224
	v_sub_f32_e32 v80, v80, v192
	v_sub_f32_e32 v81, v81, v192
	v_sub_f32_e32 v82, v82, v192
	v_sub_f32_e32 v83, v83, v192
	s_waitcnt lgkmcnt(10)
	v_mfma_f32_32x32x16_bf16 v[32:47], v[2:5], v[196:199], v[32:47]
	ds_read_b64_tr_b16 v[220:221], v13 offset:32768
	ds_read_b64_tr_b16 v[222:223], v13 offset:34816
	v_sub_f32_e32 v84, v84, v192
	v_sub_f32_e32 v85, v85, v192
	v_sub_f32_e32 v86, v86, v192
	v_sub_f32_e32 v87, v87, v192
	s_waitcnt lgkmcnt(9)
	v_mfma_f32_32x32x16_bf16 v[32:47], v[6:9], v[204:207], v[32:47]
	ds_read_b64_tr_b16 v[224:225], v13 offset:36864
	ds_read_b64_tr_b16 v[226:227], v13 offset:38912
	v_sub_f32_e32 v104, v104, v192
	v_sub_f32_e32 v105, v105, v192
	v_sub_f32_e32 v106, v106, v192
	v_sub_f32_e32 v107, v107, v192
	s_waitcnt lgkmcnt(8)
	v_mfma_f32_32x32x16_bf16 v[32:47], v[212:215], v[200:203], v[32:47]
	ds_read_b64_tr_b16 v[228:229], v13 offset:40960
	ds_read_b64_tr_b16 v[230:231], v13 offset:43008
	s_add_i32 m0, s33, 0xc00
	s_nop 0
	global_load_lds_dwordx4 v191, s[28:29]
	v_sub_f32_e32 v108, v108, v192
	v_sub_f32_e32 v109, v109, v192
	v_sub_f32_e32 v110, v110, v192
	v_sub_f32_e32 v111, v111, v192
	s_waitcnt lgkmcnt(7)
	v_mfma_f32_32x32x16_bf16 v[32:47], v[216:219], v[208:211], v[32:47]
	ds_read_b64_tr_b16 v[232:233], v13 offset:45056
	ds_read_b64_tr_b16 v[234:235], v13 offset:47104
	v_sub_f32_e32 v88, v88, v192
	v_sub_f32_e32 v89, v89, v192
	v_sub_f32_e32 v90, v90, v192
	v_sub_f32_e32 v91, v91, v192
	s_waitcnt lgkmcnt(6)
	v_mfma_f32_32x32x16_bf16 v[16:31], v[220:223], v[196:199], v[16:31]
	v_add_u32_e32 v15, v14, v175
	ds_read_b128 v[2:5], v15
	v_sub_f32_e32 v92, v92, v192
	v_sub_f32_e32 v93, v93, v192
	v_sub_f32_e32 v94, v94, v192
	v_sub_f32_e32 v95, v95, v192
	s_waitcnt lgkmcnt(5)
	v_mfma_f32_32x32x16_bf16 v[16:31], v[224:227], v[204:207], v[16:31]
	ds_read_b128 v[6:9], v15 offset:8192
	s_add_i32 m0, s72, s77
	s_nop 0
	global_load_lds_dword v172, s[68:69]
	s_waitcnt lgkmcnt(4)
	v_mfma_f32_32x32x16_bf16 v[16:31], v[228:231], v[200:203], v[16:31]
	v_add_u32_e32 v15, v14, v176
	ds_read_b128 v[212:215], v15
	s_waitcnt lgkmcnt(3)
	v_mfma_f32_32x32x16_bf16 v[16:31], v[232:235], v[208:211], v[16:31]
	ds_read_b128 v[216:219], v15 offset:8192
	s_waitcnt lgkmcnt(3)
	v_mfma_f32_32x32x16_bf16 v[96:111], v[2:5], v[112:115], v[96:111]
	v_add_u32_e32 v15, v14, v177
	ds_read_b128 v[220:223], v15
	s_waitcnt lgkmcnt(3)
	v_mfma_f32_32x32x16_bf16 v[80:95], v[6:9], v[112:115], v[80:95]
	ds_read_b128 v[224:227], v15 offset:8192
	s_waitcnt lgkmcnt(3)
	v_mfma_f32_32x32x16_bf16 v[96:111], v[212:215], v[116:119], v[96:111]
	v_add_u32_e32 v15, v14, v178
	ds_read_b128 v[228:231], v15
	s_waitcnt lgkmcnt(3)
	v_mfma_f32_32x32x16_bf16 v[80:95], v[216:219], v[116:119], v[80:95]
	ds_read_b128 v[232:235], v15 offset:8192
	s_waitcnt lgkmcnt(3)
	v_mfma_f32_32x32x16_bf16 v[96:111], v[220:223], v[120:123], v[96:111]
	v_add_u32_e32 v15, v14, v179
	ds_read_b128 v[2:5], v15
	s_waitcnt lgkmcnt(3)
	v_mfma_f32_32x32x16_bf16 v[80:95], v[224:227], v[120:123], v[80:95]
	ds_read_b128 v[6:9], v15 offset:8192
	s_waitcnt lgkmcnt(3)
	v_mfma_f32_32x32x16_bf16 v[96:111], v[228:231], v[124:127], v[96:111]
	v_add_u32_e32 v15, v14, v180
	ds_read_b128 v[212:215], v15
	s_waitcnt lgkmcnt(3)
	v_mfma_f32_32x32x16_bf16 v[80:95], v[232:235], v[124:127], v[80:95]
	ds_read_b128 v[216:219], v15 offset:8192
	s_waitcnt lgkmcnt(3)
	v_mfma_f32_32x32x16_bf16 v[96:111], v[2:5], v[128:131], v[96:111]
	v_add_u32_e32 v15, v14, v181
	ds_read_b128 v[220:223], v15
	s_waitcnt lgkmcnt(3)
	v_mfma_f32_32x32x16_bf16 v[80:95], v[6:9], v[128:131], v[80:95]
	ds_read_b128 v[224:227], v15 offset:8192
	s_waitcnt lgkmcnt(3)
	v_mfma_f32_32x32x16_bf16 v[96:111], v[212:215], v[132:135], v[96:111]
	v_add_u32_e32 v15, v14, v182
	ds_read_b128 v[228:231], v15
	s_waitcnt lgkmcnt(3)
	v_mfma_f32_32x32x16_bf16 v[80:95], v[216:219], v[132:135], v[80:95]
	ds_read_b128 v[232:235], v15 offset:8192
	s_waitcnt lgkmcnt(0)
	s_waitcnt vmcnt(5)
	s_barrier
	v_mfma_f32_32x32x16_bf16 v[96:111], v[220:223], v[136:139], v[96:111]
	v_mfma_f32_32x32x16_bf16 v[80:95], v[224:227], v[136:139], v[80:95]
	v_mfma_f32_32x32x16_bf16 v[96:111], v[228:231], v[140:143], v[96:111]
	v_mfma_f32_32x32x16_bf16 v[80:95], v[232:235], v[140:143], v[80:95]
	s_nop 7
	s_branch .Lfx_h2_fast

.Lfx_h2_invis:
	s_add_i32 m0, s74, s77
	s_nop 0
	global_load_lds_dwordx4 v188, s[30:31]
	global_load_lds_dwordx4 v188, s[30:31] offset:1024
	global_load_lds_dwordx4 v188, s[30:31] offset:2048
	global_load_lds_dwordx4 v188, s[30:31] offset:3072
	s_waitcnt vmcnt(4)
	s_branch .Lfx_h2_done
.Lfx_h2_fast:
	s_nop 1
	s_add_i32 m0, s74, s77
	s_nop 0
	global_load_lds_dwordx4 v188, s[30:31]
	v_max3_f32 v0, v96, v97, v80
	v_max3_f32 v2, v98, v99, v81
	v_max3_f32 v0, v0, v82, v83
	v_max3_f32 v2, v2, v102, v103
	v_max3_f32 v0, v0, v100, v101
	v_max3_f32 v2, v2, v86, v87
	v_max3_f32 v0, v0, v84, v85
	v_max3_f32 v2, v2, v106, v107
	v_max3_f32 v0, v0, v104, v105
	v_max3_f32 v2, v2, v90, v91
	v_max3_f32 v0, v0, v88, v89
	v_max3_f32 v2, v2, v110, v111
	v_max3_f32 v0, v0, v108, v109
	v_max3_f32 v2, v2, v94, v95
	v_max3_f32 v0, v0, v92, v93
	v_max_f32_e32 v2, v2, v2
	v_max_f32_e32 v0, v0, v0
	v_max_f32_e32 v0, v0, v2
	v_mov_b32_e32 v2, v0
	s_nop 1
	v_permlane32_swap_b32_e32 v0, v2
	v_max_f32_e32 v2, v2, v2
	v_max_f32_e32 v0, v0, v0
	v_max_f32_e32 v0, v0, v2
	v_cmp_lt_f32_e32 vcc, 0x41000000, v0
	s_cbranch_vccz .Lfx_sm_exp_f
	v_max_f32_e32 v0, 0, v0
	v_add_f32_e32 v192, v192, v0
	v_exp_f32_e64 v2, -v0
	v_sub_f32_e32 v96, v96, v0
	v_sub_f32_e32 v97, v97, v0
	v_sub_f32_e32 v98, v98, v0
	v_sub_f32_e32 v99, v99, v0
	v_sub_f32_e32 v100, v100, v0
	v_sub_f32_e32 v101, v101, v0
	v_sub_f32_e32 v102, v102, v0
	v_sub_f32_e32 v103, v103, v0
	v_sub_f32_e32 v104, v104, v0
	v_sub_f32_e32 v105, v105, v0
	v_sub_f32_e32 v106, v106, v0
	v_sub_f32_e32 v107, v107, v0
	v_sub_f32_e32 v108, v108, v0
	v_sub_f32_e32 v109, v109, v0
	v_sub_f32_e32 v110, v110, v0
	v_sub_f32_e32 v111, v111, v0
	v_sub_f32_e32 v80, v80, v0
	v_sub_f32_e32 v81, v81, v0
	v_sub_f32_e32 v82, v82, v0
	v_sub_f32_e32 v83, v83, v0
	v_sub_f32_e32 v84, v84, v0
	v_sub_f32_e32 v85, v85, v0
	v_sub_f32_e32 v86, v86, v0
	v_sub_f32_e32 v87, v87, v0
	v_sub_f32_e32 v88, v88, v0
	v_sub_f32_e32 v89, v89, v0
	v_sub_f32_e32 v90, v90, v0
	v_sub_f32_e32 v91, v91, v0
	v_sub_f32_e32 v92, v92, v0
	v_sub_f32_e32 v93, v93, v0
	v_sub_f32_e32 v94, v94, v0
	v_sub_f32_e32 v95, v95, v0
	v_mul_f32_e32 v162, v162, v2
	v_pk_mul_f32 v[78:79], v[78:79], v[2:3] op_sel_hi:[1,0]
	v_pk_mul_f32 v[76:77], v[76:77], v[2:3] op_sel_hi:[1,0]
	v_pk_mul_f32 v[74:75], v[74:75], v[2:3] op_sel_hi:[1,0]
	v_pk_mul_f32 v[72:73], v[72:73], v[2:3] op_sel_hi:[1,0]
	v_pk_mul_f32 v[70:71], v[70:71], v[2:3] op_sel_hi:[1,0]
	v_pk_mul_f32 v[68:69], v[68:69], v[2:3] op_sel_hi:[1,0]
	v_pk_mul_f32 v[66:67], v[66:67], v[2:3] op_sel_hi:[1,0]
	v_pk_mul_f32 v[64:65], v[64:65], v[2:3] op_sel_hi:[1,0]
	v_pk_mul_f32 v[62:63], v[62:63], v[2:3] op_sel_hi:[1,0]
	v_pk_mul_f32 v[60:61], v[60:61], v[2:3] op_sel_hi:[1,0]
	v_pk_mul_f32 v[58:59], v[58:59], v[2:3] op_sel_hi:[1,0]
	v_pk_mul_f32 v[56:57], v[56:57], v[2:3] op_sel_hi:[1,0]
	v_pk_mul_f32 v[54:55], v[54:55], v[2:3] op_sel_hi:[1,0]
	v_pk_mul_f32 v[52:53], v[52:53], v[2:3] op_sel_hi:[1,0]
	v_pk_mul_f32 v[50:51], v[50:51], v[2:3] op_sel_hi:[1,0]
	v_pk_mul_f32 v[48:49], v[48:49], v[2:3] op_sel_hi:[1,0]
	v_pk_mul_f32 v[46:47], v[46:47], v[2:3] op_sel_hi:[1,0]
	v_pk_mul_f32 v[44:45], v[44:45], v[2:3] op_sel_hi:[1,0]
	v_pk_mul_f32 v[42:43], v[42:43], v[2:3] op_sel_hi:[1,0]
	v_pk_mul_f32 v[40:41], v[40:41], v[2:3] op_sel_hi:[1,0]
	v_pk_mul_f32 v[38:39], v[38:39], v[2:3] op_sel_hi:[1,0]
	v_pk_mul_f32 v[36:37], v[36:37], v[2:3] op_sel_hi:[1,0]
	v_pk_mul_f32 v[34:35], v[34:35], v[2:3] op_sel_hi:[1,0]
	v_pk_mul_f32 v[32:33], v[32:33], v[2:3] op_sel_hi:[1,0]
	v_pk_mul_f32 v[30:31], v[30:31], v[2:3] op_sel_hi:[1,0]
	v_pk_mul_f32 v[28:29], v[28:29], v[2:3] op_sel_hi:[1,0]
	v_pk_mul_f32 v[26:27], v[26:27], v[2:3] op_sel_hi:[1,0]
	v_pk_mul_f32 v[24:25], v[24:25], v[2:3] op_sel_hi:[1,0]
	v_pk_mul_f32 v[22:23], v[22:23], v[2:3] op_sel_hi:[1,0]
	v_pk_mul_f32 v[20:21], v[20:21], v[2:3] op_sel_hi:[1,0]
	v_pk_mul_f32 v[18:19], v[18:19], v[2:3] op_sel_hi:[1,0]
	v_pk_mul_f32 v[16:17], v[16:17], v[2:3] op_sel_hi:[1,0]
.Lfx_sm_exp_f:
	v_exp_f32_e32 v96, v96
	v_exp_f32_e32 v97, v97
	v_exp_f32_e32 v98, v98
	global_load_lds_dwordx4 v188, s[30:31] offset:1024
	v_exp_f32_e32 v99, v99
	v_exp_f32_e32 v100, v100
	v_cvt_pk_bf16_f32 v196, v96, v97
	v_add_f32_e32 v96, v96, v97
	v_exp_f32_e32 v101, v101
	v_cvt_pk_bf16_f32 v197, v98, v99
	v_add_f32_e32 v98, v98, v99
	v_exp_f32_e32 v102, v102
	v_cvt_pk_bf16_f32 v198, v100, v101
	v_add_f32_e32 v100, v100, v101
	v_exp_f32_e32 v103, v103
	v_add_f32_e32 v96, v96, v98
	v_exp_f32_e32 v104, v104
	v_exp_f32_e32 v105, v105
	v_cvt_pk_bf16_f32 v199, v102, v103
	v_add_f32_e32 v102, v102, v103
	global_load_lds_dwordx4 v188, s[30:31] offset:2048
	v_exp_f32_e32 v106, v106
	v_cvt_pk_bf16_f32 v204, v104, v105
	v_add_f32_e32 v104, v104, v105
	v_exp_f32_e32 v107, v107
	v_add_f32_e32 v100, v100, v102
	v_exp_f32_e32 v108, v108
	v_exp_f32_e32 v109, v109
	v_cvt_pk_bf16_f32 v205, v106, v107
	v_add_f32_e32 v106, v106, v107
	v_exp_f32_e32 v110, v110
	v_cvt_pk_bf16_f32 v206, v108, v109
	v_add_f32_e32 v108, v108, v109
	v_exp_f32_e32 v111, v111
	v_add_f32_e32 v104, v104, v106
	v_add_f32_e32 v96, v96, v100
	v_exp_f32_e32 v80, v80
	global_load_lds_dwordx4 v188, s[30:31] offset:3072
	v_cvt_pk_bf16_f32 v207, v110, v111
	v_add_f32_e32 v110, v110, v111
	v_exp_f32_e32 v81, v81
	v_exp_f32_e32 v82, v82
	v_exp_f32_e32 v83, v83
	v_add_f32_e32 v108, v108, v110
	v_cvt_pk_bf16_f32 v200, v80, v81
	v_exp_f32_e32 v84, v84
	v_add_f32_e32 v80, v80, v81
	v_cvt_pk_bf16_f32 v201, v82, v83
	v_exp_f32_e32 v85, v85
	v_add_f32_e32 v82, v82, v83
	v_add_f32_e32 v104, v104, v108
	v_exp_f32_e32 v86, v86
	v_cvt_pk_bf16_f32 v202, v84, v85
	v_add_f32_e32 v84, v84, v85
	v_exp_f32_e32 v87, v87
	v_add_f32_e32 v80, v80, v82
	v_add_f32_e32 v96, v96, v104
	s_add_i32 s64, s76, s51
	v_add_u32_e32 v10, s64, v183
	ds_read_b64_tr_b16 v[2:3], v10 offset:32768
	ds_read_b64_tr_b16 v[4:5], v10 offset:34816
	ds_read_b64_tr_b16 v[6:7], v10 offset:36864
	ds_read_b64_tr_b16 v[8:9], v10 offset:38912
	ds_read_b64_tr_b16 v[212:213], v10 offset:40960
	ds_read_b64_tr_b16 v[214:215], v10 offset:43008
	ds_read_b64_tr_b16 v[216:217], v10 offset:45056
	ds_read_b64_tr_b16 v[218:219], v10 offset:47104
	v_exp_f32_e32 v88, v88
	v_cvt_pk_bf16_f32 v203, v86, v87
	v_add_f32_e32 v86, v86, v87
	v_exp_f32_e32 v89, v89
	v_exp_f32_e32 v90, v90
	v_exp_f32_e32 v91, v91
	v_add_f32_e32 v84, v84, v86
	v_cvt_pk_bf16_f32 v208, v88, v89
	v_exp_f32_e32 v92, v92
	v_add_f32_e32 v88, v88, v89
	v_cvt_pk_bf16_f32 v209, v90, v91
	v_exp_f32_e32 v93, v93
	v_add_f32_e32 v90, v90, v91
	v_add_f32_e32 v80, v80, v84
	v_exp_f32_e32 v94, v94
	v_cvt_pk_bf16_f32 v210, v92, v93
	v_add_f32_e32 v92, v92, v93
	v_exp_f32_e32 v95, v95
	v_add_f32_e32 v88, v88, v90
	v_cvt_pk_bf16_f32 v211, v94, v95
	v_add_f32_e32 v94, v94, v95
	v_add_f32_e32 v92, v92, v94
	v_add_f32_e32 v88, v88, v92
	v_add_f32_e32 v80, v80, v88
	v_add_f32_e32 v96, v96, v80
	v_add_f32_e32 v162, v162, v96
	s_waitcnt vmcnt(4)
